# removed compiler-inserted vmcnt(0) at the P1 in-projection K-loop head (source protocol uses counted vmcnt(8))
# speedup vs baseline: 1.0007x; 1.0007x over previous
; #define PG8_STAGE(bufoff, gbase, voff) do { _Pragma("unroll") for (int _i = 0; _i < 2; ++_i) \
;         __builtin_amdgcn_global_load_lds((const unsigned*)((const char*)(gbase) + (voff)[_i]), (PG8_LAS unsigned*)(lds + (bufoff) + ldsw + _i * 8192), 16, 0, 0); } while (0)
; #define PG8_LDA(dst, b, h) do { _Pragma("unroll") for (int m = 0; m < 4; ++m) _Pragma("unroll") for (int k = 0; k < 2; ++k) dst[m][k] = *(const PG8_LAS bf16x8*)(lds + PG8_SA(b, h) + aoff + m * 2048 + k * 1024); } while (0)
; #define PG8_LDB(dst, b, h) do { _Pragma("unroll") for (int n = 0; n < 2; ++n) _Pragma("unroll") for (int k = 0; k < 2; ++k) dst[n][k] = *(const PG8_LAS bf16x8*)(lds + PG8_SB(b, h) + boff + n * 2048 + k * 1024); } while (0)
; #define PG8_MMA(ai, bj, At, Bt) do { __builtin_amdgcn_s_setprio(1); _Pragma("unroll") for (int m = 0; m < 4; ++m) _Pragma("unroll") for (int n = 0; n < 2; ++n) _Pragma("unroll") for (int k = 0; k < 2; ++k) \
;         acc[ai][bj][m][n] = __builtin_amdgcn_mfma_f32_16x16x32_bf16(Bt[n][k], At[m][k], acc[ai][bj][m][n], 0, 0, 0); __builtin_amdgcn_s_setprio(0); } while (0)
; #define PG8_WAIT_V(n) asm volatile("s_waitcnt vmcnt(" #n ")" ::: "memory")
; #define PG8_WAIT_L(n) asm volatile("s_waitcnt lgkmcnt(" #n ")" ::: "memory")
; template <class Epi, class Sched, bool ALIGN_EPI = false, bool SP2 = false>
; __device__ __forceinline__ void gemm_phase(PG8_LAS unsigned char* lds, const Gemm g, const Sched& S, const Epi& E) {
;     ...
;             const bool last = (t == nt - 2);
;             const char* a1 = cA + (size_t)(t + 1) * kstep;
;             const char* a2 = last ? nA : cA + (size_t)(t + 2) * kstep; const char* b2 = last ? nB : cB + (size_t)(t + 2) * kstep;
;             const char* a3 = a2 + kstep; const char* b3 = b2 + kstep;
;             if (last && has_next) S.a_ready(nxt);
;             if constexpr (SP2) {
;             PG8_LDB(B0, 0, 0); PG8_LDB(B1, 0, 1); PG8_SCHED; PG8_LDA(At, 0, 0); PG8_STAGE(PG8_SA(1, 1), a1 + hstep, voffA);
;             PG8_WAIT_V(8); PG8_WAIT_L(0); PG8_BAR; PG8_MMA(0, 0, At, B0); PG8_MMA(0, 1, At, B1); PG8_BAR; PG8_SCHED;
;             PG8_LDA(At, 0, 1); PG8_STAGE(PG8_SB(0, 0), b2, voffB); PG8_STAGE(PG8_SB(0, 1), b2 + hstep, voffB); PG8_STAGE(PG8_SA(0, 0), a2, voffA);
;             PG8_WAIT_V(8); PG8_WAIT_L(0); PG8_BAR; PG8_MMA(1, 0, At, B0); PG8_MMA(1, 1, At, B1); PG8_BAR; PG8_SCHED;
.LBB0_119:
	ds_read_b128 v[56:59], v167
	ds_read_b128 v[60:63], v167 offset:1024
	ds_read_b128 v[136:139], v167 offset:2048
	ds_read_b128 v[158:161], v167 offset:3072
	ds_read_b128 v[170:173], v168
	ds_read_b128 v[174:177], v168 offset:1024
	ds_read_b128 v[178:181], v168 offset:2048
	ds_read_b128 v[182:185], v168 offset:3072
	s_add_u32 s26, s24, 0xfffc0080
	s_addc_u32 s27, s25, -1
	s_cmp_eq_u32 s50, 12
	s_cselect_b32 s29, s5, s27
	s_cselect_b32 s28, s7, s26
	s_cselect_b32 s27, s17, s37
	s_cselect_b32 s26, s19, s36
	v_lshl_add_u64 v[162:163], s[24:25], 0, v[150:151]
	s_add_i32 m0, s31, 0xc000
	ds_read_b128 v[186:189], v169
	ds_read_b128 v[194:197], v169 offset:1024
	ds_read_b128 v[198:201], v169 offset:2048
	ds_read_b128 v[202:205], v169 offset:3072
	ds_read_b128 v[206:209], v169 offset:4096
	ds_read_b128 v[210:213], v169 offset:5120
	ds_read_b128 v[214:217], v169 offset:6144
	ds_read_b128 v[218:221], v169 offset:7168
	global_load_lds_dwordx4 v[162:163], off
	v_lshl_add_u64 v[162:163], s[24:25], 0, v[152:153]
	s_add_i32 m0, s31, 0xe000
	s_nop 0
	global_load_lds_dwordx4 v[162:163], off
	s_waitcnt vmcnt(8)
	s_waitcnt lgkmcnt(0)
	s_barrier
	s_setprio 1
	s_waitcnt lgkmcnt(0)
	v_mfma_f32_16x16x32_bf16 v[132:135], v[56:59], v[186:189], v[132:135]
	v_mfma_f32_16x16x32_bf16 v[128:131], v[136:139], v[186:189], v[128:131]
	v_mfma_f32_16x16x32_bf16 v[116:119], v[56:59], v[198:201], v[116:119]
	v_mfma_f32_16x16x32_bf16 v[112:115], v[136:139], v[198:201], v[112:115]
	v_mfma_f32_16x16x32_bf16 v[100:103], v[56:59], v[206:209], v[100:103]
	v_mfma_f32_16x16x32_bf16 v[96:99], v[136:139], v[206:209], v[96:99]
	v_mfma_f32_16x16x32_bf16 v[84:87], v[56:59], v[214:217], v[84:87]
	v_mfma_f32_16x16x32_bf16 v[80:83], v[136:139], v[214:217], v[80:83]
	v_mfma_f32_16x16x32_bf16 v[132:135], v[60:63], v[194:197], v[132:135]
	v_mfma_f32_16x16x32_bf16 v[128:131], v[158:161], v[194:197], v[128:131]
	v_mfma_f32_16x16x32_bf16 v[116:119], v[60:63], v[202:205], v[116:119]
	v_mfma_f32_16x16x32_bf16 v[112:115], v[158:161], v[202:205], v[112:115]
	v_mfma_f32_16x16x32_bf16 v[100:103], v[60:63], v[210:213], v[100:103]
	v_mfma_f32_16x16x32_bf16 v[96:99], v[158:161], v[210:213], v[96:99]
	v_mfma_f32_16x16x32_bf16 v[84:87], v[60:63], v[218:221], v[84:87]
	v_mfma_f32_16x16x32_bf16 v[80:83], v[158:161], v[218:221], v[80:83]
	s_setprio 0
	s_setprio 1
	v_mfma_f32_16x16x32_bf16 v[124:127], v[170:173], v[186:189], v[124:127]
	v_mfma_f32_16x16x32_bf16 v[120:123], v[178:181], v[186:189], v[120:123]
	v_mfma_f32_16x16x32_bf16 v[108:111], v[170:173], v[198:201], v[108:111]
	v_mfma_f32_16x16x32_bf16 v[104:107], v[178:181], v[198:201], v[104:107]
	v_mfma_f32_16x16x32_bf16 v[92:95], v[170:173], v[206:209], v[92:95]
	v_mfma_f32_16x16x32_bf16 v[88:91], v[178:181], v[206:209], v[88:91]
	v_mfma_f32_16x16x32_bf16 v[76:79], v[170:173], v[214:217], v[76:79]
	v_mfma_f32_16x16x32_bf16 v[72:75], v[178:181], v[214:217], v[72:75]
	v_mfma_f32_16x16x32_bf16 v[124:127], v[174:177], v[194:197], v[124:127]
	v_mfma_f32_16x16x32_bf16 v[120:123], v[182:185], v[194:197], v[120:123]
	v_mfma_f32_16x16x32_bf16 v[108:111], v[174:177], v[202:205], v[108:111]
	v_mfma_f32_16x16x32_bf16 v[104:107], v[182:185], v[202:205], v[104:107]
	v_mfma_f32_16x16x32_bf16 v[92:95], v[174:177], v[210:213], v[92:95]
	v_mfma_f32_16x16x32_bf16 v[88:91], v[182:185], v[210:213], v[88:91]
	v_mfma_f32_16x16x32_bf16 v[76:79], v[174:177], v[218:221], v[76:79]
	v_mfma_f32_16x16x32_bf16 v[72:75], v[182:185], v[218:221], v[72:75]
	s_setprio 0
	s_barrier
	s_add_i32 s51, s88, s58
	v_lshl_add_u64 v[162:163], s[26:27], 0, v[142:143]
	s_mov_b32 m0, s51
	ds_read_b128 v[186:189], v169 offset:16384
	ds_read_b128 v[194:197], v169 offset:17408
	ds_read_b128 v[198:201], v169 offset:18432
	ds_read_b128 v[202:205], v169 offset:19456
	ds_read_b128 v[206:209], v169 offset:20480
	ds_read_b128 v[210:213], v169 offset:21504
	ds_read_b128 v[214:217], v169 offset:22528
	ds_read_b128 v[218:221], v169 offset:23552
	global_load_lds_dwordx4 v[162:163], off
	s_add_i32 m0, s51, 0x2000
	s_add_u32 s76, s26, 0x40000
	v_lshl_add_u64 v[222:223], s[26:27], 0, v[146:147]
	s_addc_u32 s77, s27, 0
	s_add_i32 s51, s89, s58
	global_load_lds_dwordx4 v[222:223], off
	v_lshl_add_u64 v[224:225], s[76:77], 0, v[142:143]
	s_mov_b32 m0, s51
	v_lshl_add_u64 v[226:227], s[28:29], 0, v[144:145]
	global_load_lds_dwordx4 v[224:225], off
	v_lshl_add_u64 v[224:225], s[76:77], 0, v[146:147]
	s_add_i32 m0, s51, 0x2000
	s_nop 0
	global_load_lds_dwordx4 v[224:225], off
	v_lshl_add_u64 v[224:225], s[28:29], 0, v[140:141]
	s_mov_b32 m0, s31
	s_nop 0
	global_load_lds_dwordx4 v[224:225], off
	s_mov_b32 m0, s0
	s_nop 0
	global_load_lds_dwordx4 v[226:227], off
	s_waitcnt vmcnt(8)
	s_waitcnt lgkmcnt(0)
	s_barrier
; #define PG8_STAGE(bufoff, gbase, voff) do { _Pragma("unroll") for (int _i = 0; _i < 2; ++_i) \
;         __builtin_amdgcn_global_load_lds((const unsigned*)((const char*)(gbase) + (voff)[_i]), (PG8_LAS unsigned*)(lds + (bufoff) + ldsw + _i * 8192), 16, 0, 0); } while (0)
; #define PG8_LDA(dst, b, h) do { _Pragma("unroll") for (int m = 0; m < 4; ++m) _Pragma("unroll") for (int k = 0; k < 2; ++k) dst[m][k] = *(const PG8_LAS bf16x8*)(lds + PG8_SA(b, h) + aoff + m * 2048 + k * 1024); } while (0)
; #define PG8_LDB(dst, b, h) do { _Pragma("unroll") for (int n = 0; n < 2; ++n) _Pragma("unroll") for (int k = 0; k < 2; ++k) dst[n][k] = *(const PG8_LAS bf16x8*)(lds + PG8_SB(b, h) + boff + n * 2048 + k * 1024); } while (0)
; #define PG8_MMA(ai, bj, At, Bt) do { __builtin_amdgcn_s_setprio(1); _Pragma("unroll") for (int m = 0; m < 4; ++m) _Pragma("unroll") for (int n = 0; n < 2; ++n) _Pragma("unroll") for (int k = 0; k < 2; ++k) \
;         acc[ai][bj][m][n] = __builtin_amdgcn_mfma_f32_16x16x32_bf16(Bt[n][k], At[m][k], acc[ai][bj][m][n], 0, 0, 0); __builtin_amdgcn_s_setprio(0); } while (0)
; #define PG8_WAIT_V(n) asm volatile("s_waitcnt vmcnt(" #n ")" ::: "memory")
; #define PG8_WAIT_L(n) asm volatile("s_waitcnt lgkmcnt(" #n ")" ::: "memory")
; #define PG8_BAR __builtin_amdgcn_s_barrier()
; #define PG8_SCHED __builtin_amdgcn_sched_barrier(0)
; template <class Epi, class Sched, bool ALIGN_EPI = false, bool SP2 = false>
; __device__ __forceinline__ void gemm_phase(PG8_LAS unsigned char* lds, const Gemm g, const Sched& S, const Epi& E) {
;     ...
;             PG8_WAIT_V(8); PG8_WAIT_L(0); PG8_BAR; PG8_MMA(1, 0, At, B0); PG8_MMA(1, 1, At, B1); PG8_BAR; PG8_SCHED;
;             PG8_LDB(B0, 1, 0); PG8_LDB(B1, 1, 1); PG8_SCHED; PG8_LDA(At, 1, 0); PG8_STAGE(PG8_SA(0, 1), a2 + hstep, voffA);
;             PG8_WAIT_V(8); PG8_WAIT_L(0); PG8_BAR; PG8_MMA(0, 0, At, B0); PG8_MMA(0, 1, At, B1); PG8_BAR; PG8_SCHED;
	s_setprio 1
	s_waitcnt lgkmcnt(0)
	v_mfma_f32_16x16x32_bf16 v[68:71], v[56:59], v[186:189], v[68:71]
	v_mfma_f32_16x16x32_bf16 v[64:67], v[136:139], v[186:189], v[64:67]
	v_mfma_f32_16x16x32_bf16 v[44:47], v[56:59], v[198:201], v[44:47]
	v_mfma_f32_16x16x32_bf16 v[40:43], v[136:139], v[198:201], v[40:43]
	v_mfma_f32_16x16x32_bf16 v[28:31], v[56:59], v[206:209], v[28:31]
	v_mfma_f32_16x16x32_bf16 v[24:27], v[136:139], v[206:209], v[24:27]
	v_mfma_f32_16x16x32_bf16 v[12:15], v[56:59], v[214:217], v[12:15]
	v_mfma_f32_16x16x32_bf16 v[8:11], v[136:139], v[214:217], v[8:11]
	v_mfma_f32_16x16x32_bf16 v[68:71], v[60:63], v[194:197], v[68:71]
	v_mfma_f32_16x16x32_bf16 v[64:67], v[158:161], v[194:197], v[64:67]
	v_mfma_f32_16x16x32_bf16 v[44:47], v[60:63], v[202:205], v[44:47]
	v_mfma_f32_16x16x32_bf16 v[40:43], v[158:161], v[202:205], v[40:43]
	v_mfma_f32_16x16x32_bf16 v[28:31], v[60:63], v[210:213], v[28:31]
	v_mfma_f32_16x16x32_bf16 v[24:27], v[158:161], v[210:213], v[24:27]
	v_mfma_f32_16x16x32_bf16 v[12:15], v[60:63], v[218:221], v[12:15]
	v_mfma_f32_16x16x32_bf16 v[8:11], v[158:161], v[218:221], v[8:11]
	s_setprio 0
	s_setprio 1
	v_mfma_f32_16x16x32_bf16 v[52:55], v[170:173], v[186:189], v[52:55]
	v_mfma_f32_16x16x32_bf16 v[48:51], v[178:181], v[186:189], v[48:51]
	v_mfma_f32_16x16x32_bf16 v[36:39], v[170:173], v[198:201], v[36:39]
	v_mfma_f32_16x16x32_bf16 v[32:35], v[178:181], v[198:201], v[32:35]
	v_mfma_f32_16x16x32_bf16 v[20:23], v[170:173], v[206:209], v[20:23]
	v_mfma_f32_16x16x32_bf16 v[16:19], v[178:181], v[206:209], v[16:19]
	v_mfma_f32_16x16x32_bf16 v[4:7], v[170:173], v[214:217], v[4:7]
	v_mfma_f32_16x16x32_bf16 v[0:3], v[178:181], v[214:217], v[0:3]
	v_mfma_f32_16x16x32_bf16 v[52:55], v[174:177], v[194:197], v[52:55]
	v_mfma_f32_16x16x32_bf16 v[48:51], v[182:185], v[194:197], v[48:51]
	v_mfma_f32_16x16x32_bf16 v[36:39], v[174:177], v[202:205], v[36:39]
	v_mfma_f32_16x16x32_bf16 v[32:35], v[182:185], v[202:205], v[32:35]
	v_mfma_f32_16x16x32_bf16 v[20:23], v[174:177], v[210:213], v[20:23]
	v_mfma_f32_16x16x32_bf16 v[16:19], v[182:185], v[210:213], v[16:19]
	v_mfma_f32_16x16x32_bf16 v[4:7], v[174:177], v[218:221], v[4:7]
	v_mfma_f32_16x16x32_bf16 v[0:3], v[182:185], v[218:221], v[0:3]
	s_setprio 0
	s_barrier
	s_add_i32 s51, 0, 0x18000
	s_add_i32 s76, 0, 0x1c000
	v_add_u32_e32 v158, s51, v165
	v_add_u32_e32 v182, s76, v165
	ds_read_b128 v[56:59], v158
	ds_read_b128 v[60:63], v158 offset:1024
	ds_read_b128 v[136:139], v158 offset:2048
	ds_read_b128 v[158:161], v158 offset:3072
	ds_read_b128 v[170:173], v182
	ds_read_b128 v[174:177], v182 offset:1024
	ds_read_b128 v[178:181], v182 offset:2048
	ds_read_b128 v[182:185], v182 offset:3072
	s_add_u32 s28, s28, 0x40000
	s_addc_u32 s29, s29, 0
	s_mov_b32 m0, s1
	v_lshl_add_u64 v[228:229], s[28:29], 0, v[140:141]
	ds_read_b128 v[186:189], v169 offset:32768
	ds_read_b128 v[194:197], v169 offset:33792
	ds_read_b128 v[198:201], v169 offset:34816
	ds_read_b128 v[202:205], v169 offset:35840
	ds_read_b128 v[206:209], v169 offset:36864
	ds_read_b128 v[210:213], v169 offset:37888
	ds_read_b128 v[214:217], v169 offset:38912
	ds_read_b128 v[218:221], v169 offset:39936
	global_load_lds_dwordx4 v[228:229], off
	v_lshl_add_u64 v[228:229], s[28:29], 0, v[144:145]
	s_mov_b32 m0, s38
	s_nop 0
	global_load_lds_dwordx4 v[228:229], off
	s_waitcnt vmcnt(8)
	s_waitcnt lgkmcnt(0)
	s_barrier
	s_setprio 1
	s_waitcnt lgkmcnt(0)
	v_mfma_f32_16x16x32_bf16 v[132:135], v[56:59], v[186:189], v[132:135]
	v_mfma_f32_16x16x32_bf16 v[128:131], v[136:139], v[186:189], v[128:131]
	v_mfma_f32_16x16x32_bf16 v[116:119], v[56:59], v[198:201], v[116:119]
	v_mfma_f32_16x16x32_bf16 v[112:115], v[136:139], v[198:201], v[112:115]
	v_mfma_f32_16x16x32_bf16 v[100:103], v[56:59], v[206:209], v[100:103]
	v_mfma_f32_16x16x32_bf16 v[96:99], v[136:139], v[206:209], v[96:99]
	v_mfma_f32_16x16x32_bf16 v[84:87], v[56:59], v[214:217], v[84:87]
	v_mfma_f32_16x16x32_bf16 v[80:83], v[136:139], v[214:217], v[80:83]
	v_mfma_f32_16x16x32_bf16 v[132:135], v[60:63], v[194:197], v[132:135]
	v_mfma_f32_16x16x32_bf16 v[128:131], v[158:161], v[194:197], v[128:131]
	v_mfma_f32_16x16x32_bf16 v[116:119], v[60:63], v[202:205], v[116:119]
	v_mfma_f32_16x16x32_bf16 v[112:115], v[158:161], v[202:205], v[112:115]
	v_mfma_f32_16x16x32_bf16 v[100:103], v[60:63], v[210:213], v[100:103]
	v_mfma_f32_16x16x32_bf16 v[96:99], v[158:161], v[210:213], v[96:99]
	v_mfma_f32_16x16x32_bf16 v[84:87], v[60:63], v[218:221], v[84:87]
	v_mfma_f32_16x16x32_bf16 v[80:83], v[158:161], v[218:221], v[80:83]
	s_setprio 0
	s_setprio 1
	v_mfma_f32_16x16x32_bf16 v[124:127], v[170:173], v[186:189], v[124:127]
	v_mfma_f32_16x16x32_bf16 v[120:123], v[178:181], v[186:189], v[120:123]
	v_mfma_f32_16x16x32_bf16 v[108:111], v[170:173], v[198:201], v[108:111]
	v_mfma_f32_16x16x32_bf16 v[104:107], v[178:181], v[198:201], v[104:107]
	v_mfma_f32_16x16x32_bf16 v[92:95], v[170:173], v[206:209], v[92:95]
	v_mfma_f32_16x16x32_bf16 v[88:91], v[178:181], v[206:209], v[88:91]
	v_mfma_f32_16x16x32_bf16 v[76:79], v[170:173], v[214:217], v[76:79]
	v_mfma_f32_16x16x32_bf16 v[72:75], v[178:181], v[214:217], v[72:75]
	v_mfma_f32_16x16x32_bf16 v[124:127], v[174:177], v[194:197], v[124:127]
	v_mfma_f32_16x16x32_bf16 v[120:123], v[182:185], v[194:197], v[120:123]
	v_mfma_f32_16x16x32_bf16 v[108:111], v[174:177], v[202:205], v[108:111]
	v_mfma_f32_16x16x32_bf16 v[104:107], v[182:185], v[202:205], v[104:107]
	v_mfma_f32_16x16x32_bf16 v[92:95], v[174:177], v[210:213], v[92:95]
	v_mfma_f32_16x16x32_bf16 v[88:91], v[182:185], v[210:213], v[88:91]
	v_mfma_f32_16x16x32_bf16 v[76:79], v[174:177], v[218:221], v[76:79]
	v_mfma_f32_16x16x32_bf16 v[72:75], v[182:185], v[218:221], v[72:75]
	s_setprio 0
	s_barrier
; #define PG8_STAGE(bufoff, gbase, voff) do { _Pragma("unroll") for (int _i = 0; _i < 2; ++_i) \
;         __builtin_amdgcn_global_load_lds((const unsigned*)((const char*)(gbase) + (voff)[_i]), (PG8_LAS unsigned*)(lds + (bufoff) + ldsw + _i * 8192), 16, 0, 0); } while (0)
; #define PG8_LDA(dst, b, h) do { _Pragma("unroll") for (int m = 0; m < 4; ++m) _Pragma("unroll") for (int k = 0; k < 2; ++k) dst[m][k] = *(const PG8_LAS bf16x8*)(lds + PG8_SA(b, h) + aoff + m * 2048 + k * 1024); } while (0)
; #define PG8_LDB(dst, b, h) do { _Pragma("unroll") for (int n = 0; n < 2; ++n) _Pragma("unroll") for (int k = 0; k < 2; ++k) dst[n][k] = *(const PG8_LAS bf16x8*)(lds + PG8_SB(b, h) + boff + n * 2048 + k * 1024); } while (0)
; template <class Epi, class Sched, bool ALIGN_EPI = false, bool SP2 = false>
; __device__ __forceinline__ void gemm_phase(PG8_LAS unsigned char* lds, const Gemm g, const Sched& S, const Epi& E) {
;     ...
;         for (int t = 0; t < nt; t += 2) {
;             const bool last = (t == nt - 2);
;             const char* a1 = cA + (size_t)(t + 1) * kstep;
;             const char* a2 = last ? nA : cA + (size_t)(t + 2) * kstep; const char* b2 = last ? nB : cB + (size_t)(t + 2) * kstep;
;             const char* a3 = a2 + kstep; const char* b3 = b2 + kstep;
;             if (last && has_next) S.a_ready(nxt);
;             if constexpr (SP2) {
;             PG8_LDB(B0, 0, 0); PG8_LDB(B1, 0, 1); PG8_SCHED; PG8_LDA(At, 0, 0); PG8_STAGE(PG8_SA(1, 1), a1 + hstep, voffA);
;             PG8_WAIT_V(8); PG8_WAIT_L(0); PG8_BAR; PG8_MMA(0, 0, At, B0); PG8_MMA(0, 1, At, B1); PG8_BAR; PG8_SCHED;
;             PG8_LDA(At, 0, 1); PG8_STAGE(PG8_SB(0, 0), b2, voffB); PG8_STAGE(PG8_SB(0, 1), b2 + hstep, voffB); PG8_STAGE(PG8_SA(0, 0), a2, voffA);
;             PG8_WAIT_V(8); PG8_WAIT_L(0); PG8_BAR; PG8_MMA(1, 0, At, B0); PG8_MMA(1, 1, At, B1); PG8_BAR; PG8_SCHED;
;             PG8_LDB(B0, 1, 0); PG8_LDB(B1, 1, 1); PG8_SCHED; PG8_LDA(At, 1, 0); PG8_STAGE(PG8_SA(0, 1), a2 + hstep, voffA);
;             PG8_WAIT_V(8); PG8_WAIT_L(0); PG8_BAR; PG8_MMA(0, 0, At, B0); PG8_MMA(0, 1, At, B1); PG8_BAR; PG8_SCHED;
;             PG8_LDA(At, 1, 1); PG8_STAGE(PG8_SB(1, 0), b3, voffB); PG8_STAGE(PG8_SB(1, 1), b3 + hstep, voffB); PG8_STAGE(PG8_SA(1, 0), a3, voffA);
;             PG8_WAIT_V(8); PG8_WAIT_L(0); PG8_BAR; PG8_MMA(1, 0, At, B0); PG8_MMA(1, 1, At, B1); PG8_BAR; PG8_SCHED;
	s_add_i32 s28, s51, s58
	v_lshl_add_u64 v[162:163], v[162:163], 0, s[10:11]
	s_mov_b32 m0, s28
	ds_read_b128 v[186:189], v169 offset:49152
	ds_read_b128 v[194:197], v169 offset:50176
	ds_read_b128 v[198:201], v169 offset:51200
	ds_read_b128 v[202:205], v169 offset:52224
	ds_read_b128 v[206:209], v169 offset:53248
	ds_read_b128 v[210:213], v169 offset:54272
	ds_read_b128 v[214:217], v169 offset:55296
	ds_read_b128 v[218:221], v169 offset:56320
	global_load_lds_dwordx4 v[162:163], off
	s_add_i32 m0, s28, 0x2000
	s_add_u32 s26, s26, 0x40080
	v_lshl_add_u64 v[162:163], v[222:223], 0, s[10:11]
	s_addc_u32 s27, s27, 0
	s_add_i32 s28, s76, s58
	global_load_lds_dwordx4 v[162:163], off
	v_lshl_add_u64 v[162:163], s[26:27], 0, v[142:143]
	s_mov_b32 m0, s28
	s_nop 0
	global_load_lds_dwordx4 v[162:163], off
	v_lshl_add_u64 v[162:163], s[26:27], 0, v[146:147]
	s_add_i32 m0, s28, 0x2000
	s_nop 0
	global_load_lds_dwordx4 v[162:163], off
	v_lshl_add_u64 v[162:163], v[224:225], 0, s[10:11]
	s_mov_b32 m0, s42
	s_nop 0
	global_load_lds_dwordx4 v[162:163], off
	v_lshl_add_u64 v[162:163], v[226:227], 0, s[10:11]
	s_mov_b32 m0, s59
	s_nop 0
	global_load_lds_dwordx4 v[162:163], off
	s_waitcnt vmcnt(8)
	s_waitcnt lgkmcnt(0)
	s_barrier
	s_setprio 1
	s_waitcnt lgkmcnt(0)
	v_mfma_f32_16x16x32_bf16 v[68:71], v[56:59], v[186:189], v[68:71]
	v_mfma_f32_16x16x32_bf16 v[64:67], v[136:139], v[186:189], v[64:67]
	v_mfma_f32_16x16x32_bf16 v[44:47], v[56:59], v[198:201], v[44:47]
	v_mfma_f32_16x16x32_bf16 v[40:43], v[136:139], v[198:201], v[40:43]
	v_mfma_f32_16x16x32_bf16 v[28:31], v[56:59], v[206:209], v[28:31]
	v_mfma_f32_16x16x32_bf16 v[24:27], v[136:139], v[206:209], v[24:27]
	v_mfma_f32_16x16x32_bf16 v[12:15], v[56:59], v[214:217], v[12:15]
	v_mfma_f32_16x16x32_bf16 v[8:11], v[136:139], v[214:217], v[8:11]
	v_mfma_f32_16x16x32_bf16 v[68:71], v[60:63], v[194:197], v[68:71]
	v_mfma_f32_16x16x32_bf16 v[64:67], v[158:161], v[194:197], v[64:67]
	v_mfma_f32_16x16x32_bf16 v[44:47], v[60:63], v[202:205], v[44:47]
	v_mfma_f32_16x16x32_bf16 v[40:43], v[158:161], v[202:205], v[40:43]
	v_mfma_f32_16x16x32_bf16 v[28:31], v[60:63], v[210:213], v[28:31]
	v_mfma_f32_16x16x32_bf16 v[24:27], v[158:161], v[210:213], v[24:27]
	v_mfma_f32_16x16x32_bf16 v[12:15], v[60:63], v[218:221], v[12:15]
	v_mfma_f32_16x16x32_bf16 v[8:11], v[158:161], v[218:221], v[8:11]
	s_setprio 0
	s_setprio 1
	v_mfma_f32_16x16x32_bf16 v[52:55], v[170:173], v[186:189], v[52:55]
	v_mfma_f32_16x16x32_bf16 v[48:51], v[178:181], v[186:189], v[48:51]
	v_mfma_f32_16x16x32_bf16 v[36:39], v[170:173], v[198:201], v[36:39]
	v_mfma_f32_16x16x32_bf16 v[32:35], v[178:181], v[198:201], v[32:35]
	v_mfma_f32_16x16x32_bf16 v[20:23], v[170:173], v[206:209], v[20:23]
	v_mfma_f32_16x16x32_bf16 v[16:19], v[178:181], v[206:209], v[16:19]
	v_mfma_f32_16x16x32_bf16 v[4:7], v[170:173], v[214:217], v[4:7]
	v_mfma_f32_16x16x32_bf16 v[0:3], v[178:181], v[214:217], v[0:3]
	v_mfma_f32_16x16x32_bf16 v[52:55], v[174:177], v[194:197], v[52:55]
	v_mfma_f32_16x16x32_bf16 v[48:51], v[182:185], v[194:197], v[48:51]
	v_mfma_f32_16x16x32_bf16 v[36:39], v[174:177], v[202:205], v[36:39]
	v_mfma_f32_16x16x32_bf16 v[32:35], v[182:185], v[202:205], v[32:35]
	v_mfma_f32_16x16x32_bf16 v[20:23], v[174:177], v[210:213], v[20:23]
	v_mfma_f32_16x16x32_bf16 v[16:19], v[182:185], v[210:213], v[16:19]
	v_mfma_f32_16x16x32_bf16 v[4:7], v[174:177], v[218:221], v[4:7]
	v_mfma_f32_16x16x32_bf16 v[0:3], v[182:185], v[218:221], v[0:3]
	s_setprio 0
	s_barrier
	s_add_i32 s50, s50, 2
	s_add_u32 s24, s24, 0x100
	s_addc_u32 s25, s25, 0
	s_add_u32 s36, s36, 0x100
	s_addc_u32 s37, s37, 0
	s_cmp_gt_u32 s50, 13
	s_cbranch_scc0 .LBB0_119
	s_and_b64 vcc, exec, s[12:13]
	s_cbranch_vccz .LBB0_122
	s_barrier
